# rwkv next-chunk prefetch fast path: per-row offset pairs kept in VGPRs for the tile, one base per array per chunk, one address instruction per load
# speedup vs baseline: 1.0074x; 1.0033x over previous
; __device__ __forceinline__ int launder(int x) { asm volatile("" : "+v"(x)); return x; }
; template <bool DUAL>
; __device__ __forceinline__ void rwkv_tile(const Params& p, int l, int tile, unsigned char* smem) {
;     ...
;   const int tid = launder(threadIdx.x), lane = tid & 63, w = tid >> 6, fr = lane & 15, fq = lane >> 4;
;   const int row = rg * 16 + w * 4 + fq;
;   const int c0 = fr * 4;
;   const int ld2 = l * 2 + d;
;   const size_t rowbase = (size_t)b * TPB;
;   const int lc = (tid & 15) * 4;
;   const float* mu0 = p.rwkv_mu + (size_t)(l * 2 + 0) * 1024 + h * 64 + lc;
;   const float* mu1 = p.rwkv_mu + (size_t)(l * 2 + 1) * 1024 + h * 64 + lc;
;   const float4 m0r = *(const float4*)mu0, m1r = *(const float4*)mu1;
;   const float4 m0k = *(const float4*)(mu0 + 256), m1k = *(const float4*)(mu1 + 256);
;   const float4 m0v = *(const float4*)(mu0 + 512), m1v = *(const float4*)(mu1 + 512);
;   const float4 ka4 = *(const float4*)(p.rwkv_k_a + ld2 * 256 + h * 64 + lc);
;   v2f sA = {0.f, 0.f}, sB = {0.f, 0.f};
;   v2f iA = {(row == c0) ? 1.f : 0.f, (row == c0 + 1) ? 1.f : 0.f}, iB = {(row == c0 + 2) ? 1.f : 0.f, (row == c0 + 3) ? 1.f : 0.f};
;   const int pcc = tid % 24, prow = tid / 24;
;   const bool pact = tid < 240;
;   const bf16_t* rbase_g = p.PR + rowbase * 1024 + (pcc >> 3) * 256 + h * 64 + (pcc & 7) * 8;
;   const bf16_t* pbase_g = p.PRE + (size_t)(pcc >> 3) * PRE_ARR + (rowbase * 2 + d) * 256 + h * 64 + (pcc & 7) * 8;
.LBB0_1409:
	s_or_b64 exec, exec, s[48:49]
	v_and_b32_e32 v101, 15, v61
	v_bfe_u32 v68, v61, 4, 2
	v_ashrrev_i32_e32 v61, 4, v61
	v_and_b32_e32 v66, -4, v61
	v_readlane_b32 s0, v253, 62
	v_lshlrev_b32_e32 v67, 2, v101
	v_lshl_add_u32 v62, v62, 1, 0
	v_add_u32_e32 v69, s0, v66
	v_or_b32_e32 v66, v69, v68
	v_cmp_eq_u32_e32 vcc, v66, v67
	v_or_b32_e32 v70, 1, v67
	v_lshl_add_u32 v105, v64, 1, v62
	v_lshl_add_u32 v106, v65, 1, v62
	v_add_u32_e32 v64, 1, v61
	v_sub_u32_e32 v65, 32, v61
	v_cndmask_b32_e64 v88, 0, 1.0, vcc
	v_cmp_eq_u32_e32 vcc, v66, v70
	v_or_b32_e32 v70, 2, v67
	v_lshlrev_b32_e32 v60, 1, v60
	s_movk_i32 s0, 0x180
	v_cndmask_b32_e64 v64, v65, v64, s[36:37]
	v_cndmask_b32_e64 v89, 0, 1.0, vcc
	v_cmp_eq_u32_e32 vcc, v66, v70
	v_add_u32_e32 v70, 0, v60
	v_mul_lo_u32 v64, v64, s0
	s_movk_i32 s1, 0x600
	v_add_u32_e32 v107, v70, v64
	v_add3_u32 v111, 0, v64, v60
	v_mul_lo_u32 v64, v61, s1
	v_add_u32_e32 v65, 17, v61
	v_sub_u32_e32 v61, 16, v61
	v_or_b32_e32 v67, 3, v67
	v_cndmask_b32_e64 v61, v61, v65, s[36:37]
	v_cndmask_b32_e64 v90, 0, 1.0, vcc
	v_cmp_eq_u32_e32 vcc, v66, v67
	v_ashrrev_i32_e32 v67, 31, v66
	v_lshl_add_u32 v104, v63, 1, v62
	v_mul_lo_u32 v63, v100, s0
	v_mul_lo_u32 v61, v61, s0
	v_readlane_b32 s0, v254, 21
	v_add_u32_e32 v71, v70, v60
	v_add_u32_e32 v112, v70, v61
	v_add3_u32 v116, 0, v61, v60
	v_lshlrev_b64 v[60:61], 1, v[66:67]
	v_readlane_b32 s1, v254, 22
	v_lshlrev_b32_e32 v72, 4, v101
	v_mov_b32_e32 v165, v164
	v_lshl_add_u64 v[84:85], s[0:1], 0, v[60:61]
	v_readlane_b32 s0, v254, 23
	v_readlane_b32 s1, v254, 24
	v_cndmask_b32_e64 v91, 0, 1.0, vcc
	v_add_u32_e32 v102, 0, v72
	v_lshl_add_u64 v[86:87], s[0:1], 0, v[60:61]
	v_add_u32_e32 v60, v69, v68
	v_readlane_b32 s0, v255, 26
	v_lshl_add_u32 v103, v66, 2, 0
	v_add_u32_e32 v108, 0xfffffe80, v107
	v_lshl_add_u32 v117, v60, 2, s0
	v_readlane_b32 s0, v255, 27
	v_add_u32_e32 v109, 0xffffff00, v107
	v_add_u32_e32 v110, 0xffffff80, v107
	v_add_u32_e32 v113, 0xfffffe80, v112
	v_add_u32_e32 v114, 0xffffff00, v112
	v_add_u32_e32 v115, 0xffffff80, v112
	v_add_u32_e32 v118, s0, v72
	s_movk_i32 s28, 0x58
	v_add_u32_e32 v119, v71, v64
	v_add_u32_e32 v120, v62, v63
	v_mov_b64_e32 v[94:95], v[164:165]
	v_mov_b64_e32 v[92:93], v[164:165]
	s_waitcnt lgkmcnt(0)
	s_barrier
	v_lshlrev_b32_e32 v242, 10, v97
	v_mov_b32_e32 v243, v164
	v_lshlrev_b32_e32 v244, 10, v98
	v_mov_b32_e32 v245, v164
	v_lshlrev_b32_e32 v246, 10, v99
	v_mov_b32_e32 v247, v164
	v_lshlrev_b32_e32 v248, 10, v100
	v_mov_b32_e32 v249, v164
	s_branch .LBB0_1411

.LBB0_1411:
	ds_read2_b64 v[60:63], v107 offset1:16
	ds_read_b64 v[72:73], v108
	ds_read2_b64 v[64:67], v107 offset0:32 offset1:48
	ds_read_b64 v[76:77], v109
	ds_read_b64 v[78:79], v110
	ds_read_b64 v[122:123], v111 offset:12928
	ds_read2_b64 v[68:71], v107 offset0:64 offset1:80
	s_add_i32 s52, s28, 1
	s_cmpk_eq_i32 s28, 0x87
	s_cbranch_scc1 .Lrw_du_nopf
	s_lshl_b32 s53, s52, 5
	s_sub_i32 s54, 0x11e0, s53
	s_and_b64 s[50:51], s[36:37], exec
	s_cselect_b32 s53, s53, s54
	s_add_i32 s54, s53, -1
	s_cmpk_eq_u32 s52, 0x87
	s_cbranch_scc1 .Lrw_du_pfslow
	s_and_saveexec_b64 s[50:51], s[42:43]
	s_ashr_i32 s101, s54, 31
	s_mov_b32 s100, s54
	s_lshl_b64 s[100:101], s[100:101], 11
	v_lshl_add_u64 v[40:41], v[80:81], 0, s[100:101]
	s_ashr_i32 s101, s53, 31
	s_mov_b32 s100, s53
	s_lshl_b64 s[100:101], s[100:101], 10
	v_lshl_add_u64 v[56:57], v[82:83], 0, s[100:101]
	v_lshl_add_u64 v[32:33], v[242:243], 1, v[40:41]
	global_load_dwordx4 v[32:35], v[32:33], off
	v_lshl_add_u64 v[28:29], v[244:245], 1, v[40:41]
	global_load_dwordx4 v[28:31], v[28:29], off
	v_lshl_add_u64 v[36:37], v[246:247], 1, v[40:41]
	global_load_dwordx4 v[36:39], v[36:37], off
	v_lshl_add_u64 v[44:45], v[242:243], 0, v[56:57]
	global_load_dwordx4 v[44:47], v[44:45], off
	v_lshl_add_u64 v[48:49], v[244:245], 0, v[56:57]
	global_load_dwordx4 v[48:51], v[48:49], off
	v_lshl_add_u64 v[52:53], v[246:247], 0, v[56:57]
	global_load_dwordx4 v[52:55], v[52:53], off
	s_mov_b64 exec, s[50:51]
	s_and_b64 exec, exec, s[44:45]
	v_lshl_add_u64 v[40:41], v[248:249], 1, v[40:41]
	global_load_dwordx4 v[40:43], v[40:41], off
	s_mov_b64 exec, s[50:51]
	s_and_b64 exec, exec, s[46:47]
	v_lshl_add_u64 v[56:57], v[248:249], 0, v[56:57]
	global_load_dwordx4 v[56:59], v[56:57], off
	s_mov_b64 exec, s[50:51]
	s_branch .Lrw_du_nopf

; template <bool DUAL>
; __device__ __forceinline__ void rwkv_tile(const Params& p, int l, int tile, unsigned char* smem) {
;     ...
;   const int pcc = tid % 24, prow = tid / 24;
;   const bool pact = tid < 240;
;   const bf16_t* rbase_g = p.PR + rowbase * 1024 + (pcc >> 3) * 256 + h * 64 + (pcc & 7) * 8;
;   const bf16_t* pbase_g = p.PRE + (size_t)(pcc >> 3) * PRE_ARR + (rowbase * 2 + d) * 256 + h * 64 + (pcc & 7) * 8;
;   uint4 pf0, pf1, pf2, pf3, pg0, pg1, pg2, pg3;
.LBB0_1467:
	s_or_b64 exec, exec, s[50:51]
	v_and_b32_e32 v98, 15, v61
	v_bfe_u32 v66, v61, 4, 2
	v_ashrrev_i32_e32 v61, 4, v61
	v_lshl_add_u32 v62, v62, 1, 0
	v_and_b32_e32 v67, -4, v61
	v_readlane_b32 s0, v253, 62
	v_lshl_add_u32 v102, v64, 1, v62
	v_lshl_add_u32 v103, v65, 1, v62
	v_add_u32_e32 v64, 1, v61
	v_sub_u32_e32 v65, 32, v61
	v_add_u32_e32 v67, s0, v67
	v_lshlrev_b32_e32 v60, 1, v60
	s_movk_i32 s0, 0x180
	v_cndmask_b32_e64 v64, v65, v64, s[36:37]
	v_add_u32_e32 v68, 0, v60
	v_mul_lo_u32 v64, v64, s0
	s_movk_i32 s1, 0x600
	v_add_u32_e32 v104, v68, v64
	v_add3_u32 v108, 0, v64, v60
	v_mul_lo_u32 v64, v61, s1
	v_add_u32_e32 v65, 17, v61
	v_sub_u32_e32 v61, 16, v61
	v_cndmask_b32_e64 v61, v61, v65, s[36:37]
	v_or_b32_e32 v88, v67, v66
	v_lshl_add_u32 v101, v63, 1, v62
	v_mul_lo_u32 v63, v96, s0
	v_mul_lo_u32 v61, v61, s0
	v_readlane_b32 s0, v254, 35
	v_ashrrev_i32_e32 v89, 31, v88
	v_readlane_b32 s1, v254, 36
	v_add_u32_e32 v69, v68, v60
	v_add3_u32 v113, 0, v61, v60
	v_lshl_add_u64 v[90:91], v[88:89], 1, s[0:1]
	v_add_u32_e32 v60, v67, v66
	v_readlane_b32 s0, v255, 26
	v_lshlrev_b32_e32 v70, 4, v98
	v_add_u32_e32 v109, v68, v61
	v_lshl_add_u32 v89, v60, 2, s0
	v_readlane_b32 s0, v255, 27
	v_mov_b32_e32 v165, v164
	v_lshlrev_b32_e32 v97, 2, v98
	v_add_u32_e32 v99, 0, v70
	v_lshl_add_u32 v100, v88, 2, 0
	v_add_u32_e32 v105, 0xfffffe80, v104
	v_add_u32_e32 v106, 0xffffff00, v104
	v_add_u32_e32 v107, 0xffffff80, v104
	v_add_u32_e32 v110, 0xfffffe80, v109
	v_add_u32_e32 v111, 0xffffff00, v109
	v_add_u32_e32 v112, 0xffffff80, v109
	v_add_u32_e32 v114, s0, v70
	v_add_u32_e32 v115, v69, v64
	v_add_u32_e32 v116, v62, v63
	v_mov_b64_e32 v[60:61], v[164:165]
	v_mov_b64_e32 v[62:63], v[164:165]
	v_readlane_b32 s28, v254, 17
	s_waitcnt vmcnt(0) lgkmcnt(0)
	s_barrier
	v_lshlrev_b32_e32 v242, 10, v93
	v_mov_b32_e32 v243, v164
	v_lshlrev_b32_e32 v244, 10, v94
	v_mov_b32_e32 v245, v164
	v_lshlrev_b32_e32 v246, 10, v95
	v_mov_b32_e32 v247, v164
	v_lshlrev_b32_e32 v248, 10, v96
	v_mov_b32_e32 v249, v164
.LBB0_1468:
	ds_read2_b64 v[64:67], v104 offset1:16
	ds_read_b64 v[76:77], v105
	ds_read2_b64 v[68:71], v104 offset0:32 offset1:48
	ds_read_b64 v[80:81], v106
	ds_read_b64 v[82:83], v107
	ds_read_b64 v[118:119], v108 offset:12928
	ds_read2_b64 v[72:75], v104 offset0:64 offset1:80
	s_add_i32 s56, s28, 1
	v_readlane_b32 s0, v254, 14
	s_cmp_ge_u32 s56, s0
	s_cbranch_scc1 .Lrw_nd_nopf
	s_lshl_b32 s57, s56, 5
	s_sub_i32 s58, 0xe0, s57
	s_and_b64 s[50:51], s[36:37], exec
	s_cselect_b32 s64, s57, s58
	s_sub_i32 s58, 0x11e0, s57
	s_and_b64 s[50:51], s[36:37], exec
	s_cselect_b32 s50, s57, s58
	s_cmp_lt_u32 s28, 7
	s_movk_i32 s0, 0x10ff
	s_cselect_b32 s57, s64, s50
	s_cselect_b32 s58, 0xff, s0
	s_cselect_b32 s59, 0, 0x100
	s_add_i32 s66, s57, -1
	s_cmp_eq_u32 s56, 7
	s_cbranch_scc1 .Lrw_nd_pfslow
	s_cmp_eq_u32 s56, 8
	s_cbranch_scc1 .Lrw_nd_pfslow
	s_cmpk_eq_u32 s56, 0x87
	s_cbranch_scc1 .Lrw_nd_pfslow
	s_and_saveexec_b64 s[50:51], s[42:43]
	s_ashr_i32 s101, s66, 31
	s_mov_b32 s100, s66
	s_lshl_b64 s[100:101], s[100:101], 11
	v_lshl_add_u64 v[40:41], v[84:85], 0, s[100:101]
	s_ashr_i32 s101, s57, 31
	s_mov_b32 s100, s57
	s_lshl_b64 s[100:101], s[100:101], 10
	v_lshl_add_u64 v[56:57], v[86:87], 0, s[100:101]
	v_lshl_add_u64 v[32:33], v[242:243], 1, v[40:41]
	global_load_dwordx4 v[32:35], v[32:33], off
	v_lshl_add_u64 v[28:29], v[244:245], 1, v[40:41]
	global_load_dwordx4 v[28:31], v[28:29], off
	v_lshl_add_u64 v[36:37], v[246:247], 1, v[40:41]
	global_load_dwordx4 v[36:39], v[36:37], off
	v_lshl_add_u64 v[44:45], v[242:243], 0, v[56:57]
	global_load_dwordx4 v[44:47], v[44:45], off
	v_lshl_add_u64 v[48:49], v[244:245], 0, v[56:57]
	global_load_dwordx4 v[48:51], v[48:49], off
	v_lshl_add_u64 v[52:53], v[246:247], 0, v[56:57]
	global_load_dwordx4 v[52:55], v[52:53], off
	s_mov_b64 exec, s[50:51]
	s_andn2_b64 exec, exec, s[46:47]
	v_lshl_add_u64 v[40:41], v[248:249], 1, v[40:41]
	global_load_dwordx4 v[40:43], v[40:41], off
	s_mov_b64 exec, s[50:51]
	s_and_b64 exec, exec, s[48:49]
	v_lshl_add_u64 v[56:57], v[248:249], 0, v[56:57]
	global_load_dwordx4 v[56:59], v[56:57], off
	s_mov_b64 exec, s[50:51]
	s_branch .Lrw_nd_nopf
